# adaLN-norm: coefficient (g, scale) loads of 5 groups issued with the row loads into fresh registers, counted waits instead of a vmcnt(0) chain
# speedup vs baseline: 1.0607x; 1.0075x over previous
; __device__ __forceinline__ void ph_norm(const Params& p_, int l, int skip_blocks) {
;     ...
;             f32x4 v0[8], v1[8], ca[8], cb[8];
; #pragma unroll
;             for (int j = 0; j < 8; ++j) { v0[j] = xr0[64 * j]; v1[j] = xr1[64 * j]; }
; #pragma unroll
;             for (int j = 0; j < 8; ++j) { const int col = (64 * j + lane) * 4; ca[j] = *(const f32x4*)(g + col) * (*(const f32x4*)(md + 2048 + col) + 1.f); cb[j] = *(const f32x4*)(md + col); }
;             asm volatile("" ::: "memory");
.LBB0_204:
	v_and_b32_e32 v0, 0x7ff, v197
	v_and_or_b32 v200, v198, s74, v0
	v_lshlrev_b32_e32 v0, 13, v200
	v_lshl_or_b32 v199, v200, 11, v181
	v_lshl_add_u64 v[2:3], v[98:99], 0, v[0:1]
	v_lshlrev_b32_e32 v0, 2, v199
	v_lshl_add_u64 v[4:5], v[98:99], 0, v[0:1]
	v_lshrrev_b32_e32 v0, 11, v197
	v_or_b32_e32 v0, s3, v0
	v_mul_u32_u24_e32 v0, 0x1800, v0
	global_load_dwordx4 v[62:65], v[2:3], off
	global_load_dwordx4 v[58:61], v[4:5], off
	global_load_dwordx4 v[54:57], v[2:3], off offset:1024
	global_load_dwordx4 v[50:53], v[4:5], off offset:1024
	global_load_dwordx4 v[46:49], v[2:3], off offset:2048
	global_load_dwordx4 v[42:45], v[4:5], off offset:2048
	global_load_dwordx4 v[38:41], v[2:3], off offset:3072
	global_load_dwordx4 v[34:37], v[4:5], off offset:3072
	v_add_co_u32_e32 v2, vcc, s74, v2
	v_lshl_add_u64 v[94:95], v[0:1], 2, s[42:43]
	s_nop 0
	v_addc_co_u32_e32 v3, vcc, 0, v3, vcc
	v_add_co_u32_e32 v4, vcc, s74, v4
	v_lshl_add_u64 v[96:97], v[94:95], 0, s[26:27]
	v_mov_b32_e32 v113, v1
	v_addc_co_u32_e32 v5, vcc, 0, v5, vcc
	v_lshl_add_u64 v[70:71], v[96:97], 0, v[112:113]
	global_load_dwordx4 v[30:33], v[2:3], off
	global_load_dwordx4 v[26:29], v[4:5], off
	global_load_dwordx4 v[22:25], v[2:3], off offset:1024
	global_load_dwordx4 v[18:21], v[4:5], off offset:1024
	global_load_dwordx4 v[14:17], v[2:3], off offset:2048
	global_load_dwordx4 v[10:13], v[4:5], off offset:2048
	global_load_dwordx4 v[6:9], v[2:3], off offset:3072
	s_nop 0
	global_load_dwordx4 v[2:5], v[4:5], off offset:3072
	v_mov_b32_e32 v115, v1
	global_load_dwordx4 v[70:73], v[70:71], off
	v_lshl_add_u64 v[86:87], v[94:95], 0, v[112:113]
	global_load_dwordx4 v[66:69], v[100:101], off
	v_lshl_add_u64 v[74:75], v[96:97], 0, v[114:115]
	v_mov_b32_e32 v117, v1
	v_lshl_add_u64 v[78:79], v[96:97], 0, v[116:117]
	v_mov_b32_e32 v119, v1
	v_lshl_add_u64 v[82:83], v[96:97], 0, v[118:119]
	v_mov_b32_e32 v121, v1
	v_mov_b32_e32 v123, v1
	v_lshl_add_u64 v[90:91], v[96:97], 0, v[122:123]
	v_mov_b32_e32 v125, v1
	v_lshl_add_u64 v[166:167], v[96:97], 0, v[124:125]
	v_mov_b32_e32 v127, v1
	global_load_dwordx4 v[210:213], v[100:101], off offset:1024
	global_load_dwordx4 v[214:217], v[74:75], off
	global_load_dwordx4 v[218:221], v[100:101], off offset:2048
	global_load_dwordx4 v[222:225], v[78:79], off
	global_load_dwordx4 v[226:229], v[100:101], off offset:3072
	global_load_dwordx4 v[230:233], v[82:83], off
	global_load_dwordx4 v[234:237], v[102:103], off
	v_lshl_add_u64 v[250:251], v[96:97], 0, v[120:121]
	global_load_dwordx4 v[238:241], v[250:251], off
	global_load_dwordx4 v[242:245], v[104:105], off
	global_load_dwordx4 v[246:249], v[90:91], off
	v_xor_b32_e32 v119, 8, v178
	s_mov_b32 s12, 0x3a000000
	s_movk_i32 s9, 0xfff
	v_add_u32_e32 v198, s24, v198
	s_waitcnt vmcnt(10)
	v_mul_f32_e32 v0, v30, v30
	v_mul_f32_e32 v113, v31, v31
	v_mul_f32_e32 v115, v32, v32
	v_pk_add_f32 v[72:73], v[72:73], 1.0 op_sel_hi:[1,0]
	v_pk_add_f32 v[70:71], v[70:71], 1.0 op_sel_hi:[1,0]
	v_pk_mul_f32 v[128:129], v[68:69], v[72:73]
	v_pk_mul_f32 v[130:131], v[66:67], v[70:71]
	global_load_dwordx4 v[66:69], v[86:87], off
	v_mul_f32_e32 v117, v33, v33
	s_waitcnt vmcnt(9)
	v_pk_add_f32 v[216:217], v[216:217], 1.0 op_sel_hi:[1,0]
	v_pk_add_f32 v[214:215], v[214:215], 1.0 op_sel_hi:[1,0]
	v_pk_mul_f32 v[132:133], v[212:213], v[216:217]
	v_pk_mul_f32 v[134:135], v[210:211], v[214:215]
	global_load_dwordx4 v[70:73], v[86:87], off offset:1024
	s_nop 0
	s_waitcnt vmcnt(8)
	v_pk_add_f32 v[224:225], v[224:225], 1.0 op_sel_hi:[1,0]
	v_pk_add_f32 v[222:223], v[222:223], 1.0 op_sel_hi:[1,0]
	v_pk_mul_f32 v[136:137], v[220:221], v[224:225]
	v_pk_mul_f32 v[138:139], v[218:219], v[222:223]
	global_load_dwordx4 v[74:77], v[86:87], off offset:2048
	s_nop 0
	s_waitcnt vmcnt(7)
	v_pk_add_f32 v[232:233], v[232:233], 1.0 op_sel_hi:[1,0]
	v_pk_add_f32 v[230:231], v[230:231], 1.0 op_sel_hi:[1,0]
	v_pk_mul_f32 v[140:141], v[228:229], v[232:233]
	v_pk_mul_f32 v[142:143], v[226:227], v[230:231]
	global_load_dwordx4 v[78:81], v[86:87], off offset:3072
	v_lshl_add_u64 v[86:87], v[96:97], 0, v[120:121]
	v_lshl_add_u64 v[96:97], v[96:97], 0, v[126:127]
	s_waitcnt vmcnt(6)
	v_pk_add_f32 v[238:239], v[238:239], 1.0 op_sel_hi:[1,0]
	v_pk_add_f32 v[240:241], v[240:241], 1.0 op_sel_hi:[1,0]
	v_pk_mul_f32 v[160:161], v[234:235], v[238:239]
	v_lshl_add_u64 v[82:83], v[94:95], 0, v[120:121]
	v_pk_mul_f32 v[144:145], v[236:237], v[240:241]
	global_load_dwordx4 v[82:85], v[82:83], off
	s_nop 0
	v_xor_b32_e32 v121, 16, v178
	s_waitcnt vmcnt(5)
	v_pk_add_f32 v[246:247], v[246:247], 1.0 op_sel_hi:[1,0]
	v_pk_add_f32 v[248:249], v[248:249], 1.0 op_sel_hi:[1,0]
	v_pk_mul_f32 v[164:165], v[242:243], v[246:247]
	v_lshl_add_u64 v[86:87], v[94:95], 0, v[122:123]
	v_pk_mul_f32 v[162:163], v[244:245], v[248:249]
	global_load_dwordx4 v[86:89], v[86:87], off
	s_nop 0
	global_load_dwordx4 v[90:93], v[106:107], off
	v_xor_b32_e32 v123, 32, v178
	global_load_dwordx4 v[166:169], v[166:167], off
	s_waitcnt vmcnt(0)
	v_pk_add_f32 v[168:169], v[168:169], 1.0 op_sel_hi:[1,0]
	v_pk_add_f32 v[170:171], v[166:167], 1.0 op_sel_hi:[1,0]
	v_pk_mul_f32 v[166:167], v[92:93], v[168:169]
	v_pk_mul_f32 v[168:169], v[90:91], v[170:171]
	v_lshl_add_u64 v[90:91], v[94:95], 0, v[124:125]
	global_load_dwordx4 v[90:93], v[90:91], off
	s_nop 0
	global_load_dwordx4 v[172:175], v[108:109], off
	global_load_dwordx4 v[202:205], v[96:97], off
	v_lshl_add_u64 v[94:95], v[94:95], 0, v[126:127]
	s_waitcnt vmcnt(0)
; __device__ __forceinline__ void ph_norm(const Params& p_, int l, int skip_blocks) {
;     ...
;             float s0 = 0.f, s1 = 0.f;
; #pragma unroll
;             for (int j = 0; j < 8; ++j) { s0 += (v0[j][0] * v0[j][0] + v0[j][1] * v0[j][1]) + (v0[j][2] * v0[j][2] + v0[j][3] * v0[j][3]); s1 += (v1[j][0] * v1[j][0] + v1[j][1] * v1[j][1]) + (v1[j][2] * v1[j][2] + v1[j][3] * v1[j][3]); }
;             s0 = wave_sum(s0); s1 = wave_sum(s1);
	v_pk_add_f32 v[176:177], v[202:203], 1.0 op_sel_hi:[1,0]
	v_pk_add_f32 v[96:97], v[204:205], 1.0 op_sel_hi:[1,0]
	v_pk_mul_f32 v[172:173], v[172:173], v[176:177]
	v_mov_b32_e32 v176, v63
	v_mov_b32_e32 v177, v55
	v_pk_mul_f32 v[170:171], v[174:175], v[96:97]
	v_mov_b32_e32 v174, v62
	v_mov_b32_e32 v175, v54
	v_pk_mul_f32 v[176:177], v[176:177], v[176:177]
	v_mov_b32_e32 v202, v65
	v_mov_b32_e32 v203, v57
	v_pk_fma_f32 v[174:175], v[174:175], v[174:175], v[176:177]
	v_mov_b32_e32 v176, v64
	v_mov_b32_e32 v177, v56
	v_pk_mul_f32 v[202:203], v[202:203], v[202:203]
	v_mov_b32_e32 v204, v61
	v_pk_fma_f32 v[176:177], v[176:177], v[176:177], v[202:203]
	v_mov_b32_e32 v202, v59
	v_mov_b32_e32 v203, v51
	v_pk_add_f32 v[174:175], v[174:175], v[176:177]
	v_mov_b32_e32 v176, v58
	v_mov_b32_e32 v177, v50
	v_pk_mul_f32 v[202:203], v[202:203], v[202:203]
	v_mov_b32_e32 v205, v53
	v_pk_fma_f32 v[176:177], v[176:177], v[176:177], v[202:203]
	v_mov_b32_e32 v202, v60
	v_mov_b32_e32 v203, v52
	v_pk_mul_f32 v[204:205], v[204:205], v[204:205]
	v_pk_add_f32 v[174:175], v[174:175], v[174:175] op_sel:[0,1] op_sel_hi:[1,0]
	v_pk_fma_f32 v[202:203], v[202:203], v[202:203], v[204:205]
	v_pk_mul_f32 v[204:205], v[46:47], v[46:47]
	v_pk_add_f32 v[176:177], v[176:177], v[202:203]
	v_pk_mul_f32 v[202:203], v[48:49], v[48:49]
	v_mov_b32_e32 v175, v0
	v_pk_mov_b32 v[206:207], v[204:205], v[202:203] op_sel:[1,0]
	v_mov_b32_e32 v205, v203
	v_pk_add_f32 v[202:203], v[206:207], v[204:205]
	v_pk_mul_f32 v[204:205], v[44:45], v[44:45]
	v_pk_add_f32 v[202:203], v[202:203], v[202:203] op_sel:[0,1] op_sel_hi:[1,0]
	v_pk_mul_f32 v[206:207], v[42:43], v[42:43]
	v_mov_b32_e32 v203, v113
	v_mul_f32_e32 v0, v39, v39
	v_pk_mov_b32 v[208:209], v[206:207], v[204:205] op_sel:[1,0]
	v_mov_b32_e32 v207, v205
	v_pk_add_f32 v[174:175], v[174:175], v[202:203]
	v_pk_fma_f32 v[202:203], v[38:39], v[38:39], v[0:1] op_sel_hi:[1,1,0]
	v_mul_f32_e32 v0, v41, v41
	v_pk_add_f32 v[204:205], v[208:209], v[206:207]
	v_pk_fma_f32 v[206:207], v[40:41], v[40:41], v[0:1] op_sel_hi:[1,1,0]
	v_mov_b32_e32 v203, v115
	v_mov_b32_e32 v207, v117
	v_pk_add_f32 v[202:203], v[202:203], v[206:207]
	v_mul_f32_e32 v0, v26, v26
	v_pk_add_f32 v[174:175], v[174:175], v[202:203]
	v_mul_f32_e32 v113, v27, v27
	v_pk_add_f32 v[176:177], v[176:177], v[176:177] op_sel:[0,1] op_sel_hi:[1,0]
	v_pk_add_f32 v[202:203], v[204:205], v[204:205] op_sel:[0,1] op_sel_hi:[1,0]
	v_mov_b32_e32 v177, v0
	v_mov_b32_e32 v203, v113
	v_mul_f32_e32 v0, v35, v35
	v_pk_add_f32 v[176:177], v[176:177], v[202:203]
	v_pk_fma_f32 v[202:203], v[34:35], v[34:35], v[0:1] op_sel_hi:[1,1,0]
	v_mul_f32_e32 v0, v37, v37
	v_mul_f32_e32 v115, v28, v28
	v_mul_f32_e32 v117, v29, v29
	v_pk_fma_f32 v[204:205], v[36:37], v[36:37], v[0:1] op_sel_hi:[1,1,0]
	v_mov_b32_e32 v203, v115
	v_mov_b32_e32 v205, v117
	v_pk_add_f32 v[202:203], v[202:203], v[204:205]
	v_pk_mul_f32 v[204:205], v[22:23], v[22:23]
	v_pk_add_f32 v[176:177], v[176:177], v[202:203]
	v_pk_mul_f32 v[202:203], v[24:25], v[24:25]
	v_mul_f32_e32 v0, v6, v6
	v_pk_mov_b32 v[206:207], v[204:205], v[202:203] op_sel:[1,0]
	v_mov_b32_e32 v205, v203
	v_pk_add_f32 v[202:203], v[206:207], v[204:205]
	v_mul_f32_e32 v113, v7, v7
	v_pk_add_f32 v[174:175], v[174:175], v[174:175] op_sel:[0,1] op_sel_hi:[1,0]
	v_pk_add_f32 v[202:203], v[202:203], v[202:203] op_sel:[0,1] op_sel_hi:[1,0]
	v_pk_mul_f32 v[204:205], v[20:21], v[20:21]
	v_pk_mul_f32 v[206:207], v[18:19], v[18:19]
	v_mov_b32_e32 v175, v0
	v_mov_b32_e32 v203, v113
	v_mul_f32_e32 v0, v15, v15
	v_pk_mov_b32 v[208:209], v[206:207], v[204:205] op_sel:[1,0]
	v_mov_b32_e32 v207, v205
	v_pk_add_f32 v[174:175], v[174:175], v[202:203]
	v_pk_fma_f32 v[202:203], v[14:15], v[14:15], v[0:1] op_sel_hi:[1,1,0]
	v_mul_f32_e32 v0, v17, v17
	v_pk_add_f32 v[204:205], v[208:209], v[206:207]
	v_mul_f32_e32 v115, v8, v8
	v_mul_f32_e32 v117, v9, v9
	v_pk_fma_f32 v[206:207], v[16:17], v[16:17], v[0:1] op_sel_hi:[1,1,0]
	v_mov_b32_e32 v203, v115
	v_mov_b32_e32 v207, v117
	v_pk_add_f32 v[202:203], v[202:203], v[206:207]
	v_mul_f32_e32 v0, v2, v2
	v_pk_add_f32 v[174:175], v[174:175], v[202:203]
	v_mul_f32_e32 v113, v3, v3
	v_pk_add_f32 v[176:177], v[176:177], v[176:177] op_sel:[0,1] op_sel_hi:[1,0]
	v_pk_add_f32 v[202:203], v[204:205], v[204:205] op_sel:[0,1] op_sel_hi:[1,0]
	v_mov_b32_e32 v177, v0
	v_mov_b32_e32 v203, v113
	v_mul_f32_e32 v0, v11, v11
	v_pk_add_f32 v[176:177], v[176:177], v[202:203]
	v_pk_fma_f32 v[202:203], v[10:11], v[10:11], v[0:1] op_sel_hi:[1,1,0]
	v_mul_f32_e32 v0, v13, v13
	v_mul_f32_e32 v115, v4, v4
	v_mul_f32_e32 v117, v5, v5
	v_pk_fma_f32 v[204:205], v[12:13], v[12:13], v[0:1] op_sel_hi:[1,1,0]
	v_mov_b32_e32 v203, v115
	v_mov_b32_e32 v205, v117
	v_and_b32_e32 v0, 64, v178
	v_pk_add_f32 v[202:203], v[202:203], v[204:205]
	v_add_u32_e32 v0, 64, v0
	v_xor_b32_e32 v113, 1, v178
	v_pk_add_f32 v[176:177], v[176:177], v[202:203]
	v_cmp_lt_i32_e32 vcc, v113, v0
	v_mov_b32_e32 v202, v176
	v_mov_b32_e32 v203, v174
	v_cndmask_b32_e32 v113, v178, v113, vcc
	v_mov_b32_e32 v174, v177
	v_lshlrev_b32_e32 v113, 2, v113
	v_pk_add_f32 v[174:175], v[202:203], v[174:175]
	ds_bpermute_b32 v177, v113, v175
	ds_bpermute_b32 v176, v113, v174
	v_xor_b32_e32 v115, 2, v178
	v_cmp_lt_i32_e32 vcc, v115, v0
	v_xor_b32_e32 v117, 4, v178
	global_load_dwordx4 v[94:97], v[94:95], off
	v_cndmask_b32_e32 v115, v178, v115, vcc
	v_lshlrev_b32_e32 v115, 2, v115
	s_waitcnt lgkmcnt(0)
	v_pk_add_f32 v[174:175], v[174:175], v[176:177]
	ds_bpermute_b32 v177, v115, v175
	ds_bpermute_b32 v176, v115, v174
	v_cmp_lt_i32_e32 vcc, v117, v0
	s_waitcnt lgkmcnt(0)
; __device__ __forceinline__ unsigned pk2(float lo, float hi) { return f2bf(lo) | (f2bf(hi) << 16); }
; __device__ __forceinline__ void ph_norm(const Params& p_, int l, int skip_blocks) {
;     ...
;             s0 = wave_sum(s0); s1 = wave_sum(s1);
;             const float r0 = rsqrtf(s0 * (1.f / DM) + 1e-6f), r1 = rsqrtf(s1 * (1.f / DM) + 1e-6f);
; #pragma unroll
;             for (int j = 0; j < 8; ++j) { const int col = (64 * j + lane) * 4;
;                 const f32x4 o0 = (v0[j] * r0) * ca[j] + cb[j], o1 = (v1[j] * r1) * ca[j] + cb[j]; u32x2 w;
;                 w.x = pk2(o0[0], o0[1]); w.y = pk2(o0[2], o0[3]); *(u32x2*)(h + (size_t)row * DM + col) = w;
;                 w.x = pk2(o1[0], o1[1]); w.y = pk2(o1[2], o1[3]); *(u32x2*)(h + (size_t)(row + stride) * DM + col) = w; }
	v_pk_add_f32 v[174:175], v[174:175], v[176:177]
	v_cndmask_b32_e32 v117, v178, v117, vcc
	v_lshlrev_b32_e32 v117, 2, v117
	ds_bpermute_b32 v177, v117, v175
	ds_bpermute_b32 v176, v117, v174
	v_cmp_lt_i32_e32 vcc, v119, v0
	s_waitcnt lgkmcnt(0)
	v_pk_add_f32 v[174:175], v[174:175], v[176:177]
	v_cndmask_b32_e32 v119, v178, v119, vcc
	v_lshlrev_b32_e32 v119, 2, v119
	ds_bpermute_b32 v177, v119, v175
	ds_bpermute_b32 v176, v119, v174
	v_cmp_lt_i32_e32 vcc, v121, v0
	s_waitcnt lgkmcnt(0)
	v_pk_add_f32 v[174:175], v[174:175], v[176:177]
	v_cndmask_b32_e32 v121, v178, v121, vcc
	v_lshlrev_b32_e32 v121, 2, v121
	ds_bpermute_b32 v177, v121, v175
	ds_bpermute_b32 v176, v121, v174
	v_cmp_lt_i32_e32 vcc, v123, v0
	s_waitcnt lgkmcnt(0)
	v_pk_add_f32 v[174:175], v[174:175], v[176:177]
	v_cndmask_b32_e32 v0, v178, v123, vcc
	v_lshlrev_b32_e32 v0, 2, v0
	ds_bpermute_b32 v177, v0, v175
	ds_bpermute_b32 v176, v0, v174
	s_waitcnt lgkmcnt(0)
	v_pk_add_f32 v[174:175], v[174:175], v[176:177]
	s_nop 0
	v_pk_fma_f32 v[174:175], v[174:175], s[12:13], v[146:147] op_sel_hi:[1,0,0]
	s_nop 0
	v_mul_f32_e32 v0, 0x4b800000, v175
	v_cmp_gt_f32_e64 s[36:37], s92, v175
	v_cmp_gt_f32_e32 vcc, s92, v174
	s_nop 0
	v_cndmask_b32_e64 v0, v175, v0, s[36:37]
	v_rsq_f32_e32 v0, v0
	s_nop 0
	v_mul_f32_e32 v113, 0x45800000, v0
	v_cndmask_b32_e64 v176, v0, v113, s[36:37]
	v_mul_f32_e32 v0, 0x4b800000, v174
	v_cndmask_b32_e32 v0, v174, v0, vcc
	v_rsq_f32_e32 v0, v0
	v_pk_mul_f32 v[62:63], v[62:63], v[176:177] op_sel_hi:[1,0]
	v_pk_mul_f32 v[64:65], v[64:65], v[176:177] op_sel_hi:[1,0]
	v_pk_fma_f32 v[62:63], v[130:131], v[62:63], v[66:67]
	v_mul_f32_e32 v113, 0x45800000, v0
	v_cndmask_b32_e32 v174, v0, v113, vcc
	v_bfe_u32 v0, v62, 16, 1
	v_add3_u32 v0, v62, v0, s14
	v_bfe_u32 v62, v63, 16, 1
	v_pk_fma_f32 v[64:65], v[128:129], v[64:65], v[68:69]
	v_lshrrev_b32_e32 v0, 16, v0
	v_add3_u32 v62, v63, v62, s14
	v_and_or_b32 v62, v62, s15, v0
	v_bfe_u32 v0, v64, 16, 1
	v_add3_u32 v0, v64, v0, s14
	v_bfe_u32 v63, v65, 16, 1
	v_pk_mul_f32 v[58:59], v[58:59], v[174:175] op_sel_hi:[1,0]
	v_lshrrev_b32_e32 v0, 16, v0
	v_add3_u32 v63, v65, v63, s14
	v_pk_fma_f32 v[58:59], v[130:131], v[58:59], v[66:67]
	v_and_or_b32 v63, v63, s15, v0
	v_lshlrev_b32_e32 v0, 12, v200
	v_lshl_add_u64 v[64:65], v[110:111], 0, v[0:1]
	v_bfe_u32 v0, v58, 16, 1
	v_pk_mul_f32 v[60:61], v[60:61], v[174:175] op_sel_hi:[1,0]
	v_add3_u32 v0, v58, v0, s14
	v_bfe_u32 v58, v59, 16, 1
	v_pk_fma_f32 v[60:61], v[128:129], v[60:61], v[68:69]
	v_lshrrev_b32_e32 v0, 16, v0
	v_add3_u32 v58, v59, v58, s14
	v_and_or_b32 v58, v58, s15, v0
	v_bfe_u32 v0, v60, 16, 1
	v_add3_u32 v0, v60, v0, s14
	v_bfe_u32 v59, v61, 16, 1
	v_lshrrev_b32_e32 v0, 16, v0
	v_add3_u32 v59, v61, v59, s14
	v_pk_mul_f32 v[54:55], v[54:55], v[176:177] op_sel_hi:[1,0]
	v_and_or_b32 v59, v59, s15, v0
	v_lshlrev_b32_e32 v0, 1, v199
	v_pk_fma_f32 v[54:55], v[134:135], v[54:55], v[70:71]
	v_lshl_add_u64 v[60:61], v[110:111], 0, v[0:1]
	v_bfe_u32 v0, v54, 16, 1
	v_pk_mul_f32 v[56:57], v[56:57], v[176:177] op_sel_hi:[1,0]
	v_add3_u32 v0, v54, v0, s14
	v_bfe_u32 v54, v55, 16, 1
	v_pk_fma_f32 v[56:57], v[132:133], v[56:57], v[72:73]
	v_lshrrev_b32_e32 v0, 16, v0
	v_add3_u32 v54, v55, v54, s14
	v_and_or_b32 v54, v54, s15, v0
	v_bfe_u32 v0, v56, 16, 1
	v_pk_mul_f32 v[50:51], v[50:51], v[174:175] op_sel_hi:[1,0]
	v_add3_u32 v0, v56, v0, s14
	v_bfe_u32 v55, v57, 16, 1
	v_pk_fma_f32 v[50:51], v[134:135], v[50:51], v[70:71]
	v_lshrrev_b32_e32 v0, 16, v0
	v_add3_u32 v55, v57, v55, s14
	v_and_or_b32 v55, v55, s15, v0
	v_bfe_u32 v0, v50, 16, 1
	v_pk_mul_f32 v[52:53], v[52:53], v[174:175] op_sel_hi:[1,0]
	v_add3_u32 v0, v50, v0, s14
	v_bfe_u32 v50, v51, 16, 1
	v_pk_fma_f32 v[52:53], v[132:133], v[52:53], v[72:73]
	v_lshrrev_b32_e32 v0, 16, v0
	v_add3_u32 v50, v51, v50, s14
	v_and_or_b32 v50, v50, s15, v0
	v_bfe_u32 v0, v52, 16, 1
	v_add3_u32 v0, v52, v0, s14
	v_bfe_u32 v51, v53, 16, 1
	v_pk_mul_f32 v[46:47], v[46:47], v[176:177] op_sel_hi:[1,0]
	v_lshrrev_b32_e32 v0, 16, v0
	v_add3_u32 v51, v53, v51, s14
	v_pk_fma_f32 v[46:47], v[138:139], v[46:47], v[74:75]
	v_and_or_b32 v51, v51, s15, v0
	v_bfe_u32 v0, v46, 16, 1
	v_pk_mul_f32 v[48:49], v[48:49], v[176:177] op_sel_hi:[1,0]
	v_add3_u32 v0, v46, v0, s14
	v_bfe_u32 v46, v47, 16, 1
	v_pk_fma_f32 v[48:49], v[136:137], v[48:49], v[76:77]
	v_lshrrev_b32_e32 v0, 16, v0
	v_add3_u32 v46, v47, v46, s14
	v_and_or_b32 v46, v46, s15, v0
	v_bfe_u32 v0, v48, 16, 1
	v_pk_mul_f32 v[42:43], v[42:43], v[174:175] op_sel_hi:[1,0]
	v_add3_u32 v0, v48, v0, s14
	v_bfe_u32 v47, v49, 16, 1
	v_pk_fma_f32 v[42:43], v[138:139], v[42:43], v[74:75]
	v_lshrrev_b32_e32 v0, 16, v0
	v_add3_u32 v47, v49, v47, s14
	v_and_or_b32 v47, v47, s15, v0
	v_bfe_u32 v0, v42, 16, 1
	v_pk_mul_f32 v[44:45], v[44:45], v[174:175] op_sel_hi:[1,0]
	v_add3_u32 v0, v42, v0, s14
	v_bfe_u32 v42, v43, 16, 1
	v_pk_fma_f32 v[44:45], v[136:137], v[44:45], v[76:77]
	v_lshrrev_b32_e32 v0, 16, v0
	v_add3_u32 v42, v43, v42, s14
	v_and_or_b32 v42, v42, s15, v0
	v_bfe_u32 v0, v44, 16, 1
	v_add3_u32 v0, v44, v0, s14
	v_bfe_u32 v43, v45, 16, 1
	v_pk_mul_f32 v[38:39], v[38:39], v[176:177] op_sel_hi:[1,0]
	v_lshrrev_b32_e32 v0, 16, v0
	v_add3_u32 v43, v45, v43, s14
	v_pk_fma_f32 v[38:39], v[142:143], v[38:39], v[78:79]
	v_and_or_b32 v43, v43, s15, v0
	v_bfe_u32 v0, v38, 16, 1
	v_pk_mul_f32 v[40:41], v[40:41], v[176:177] op_sel_hi:[1,0]
	v_add3_u32 v0, v38, v0, s14
	v_bfe_u32 v38, v39, 16, 1
	v_pk_fma_f32 v[40:41], v[140:141], v[40:41], v[80:81]
	v_lshrrev_b32_e32 v0, 16, v0
	v_add3_u32 v38, v39, v38, s14
	v_and_or_b32 v38, v38, s15, v0
	v_bfe_u32 v0, v40, 16, 1
	v_pk_mul_f32 v[34:35], v[34:35], v[174:175] op_sel_hi:[1,0]
; __device__ __forceinline__ unsigned pk2(float lo, float hi) { return f2bf(lo) | (f2bf(hi) << 16); }
; __device__ __forceinline__ void ph_norm(const Params& p_, int l, int skip_blocks) {
;     ...
; #pragma unroll
;             for (int j = 0; j < 8; ++j) { const int col = (64 * j + lane) * 4;
;                 const f32x4 o0 = (v0[j] * r0) * ca[j] + cb[j], o1 = (v1[j] * r1) * ca[j] + cb[j]; u32x2 w;
;                 w.x = pk2(o0[0], o0[1]); w.y = pk2(o0[2], o0[3]); *(u32x2*)(h + (size_t)row * DM + col) = w;
;                 w.x = pk2(o1[0], o1[1]); w.y = pk2(o1[2], o1[3]); *(u32x2*)(h + (size_t)(row + stride) * DM + col) = w; }
	v_add3_u32 v0, v40, v0, s14
	v_bfe_u32 v39, v41, 16, 1
	v_pk_fma_f32 v[34:35], v[142:143], v[34:35], v[78:79]
	v_lshrrev_b32_e32 v0, 16, v0
	v_add3_u32 v39, v41, v39, s14
	v_and_or_b32 v39, v39, s15, v0
	v_bfe_u32 v0, v34, 16, 1
	v_pk_mul_f32 v[36:37], v[36:37], v[174:175] op_sel_hi:[1,0]
	v_add3_u32 v0, v34, v0, s14
	v_bfe_u32 v34, v35, 16, 1
	v_pk_fma_f32 v[36:37], v[140:141], v[36:37], v[80:81]
	v_lshrrev_b32_e32 v0, 16, v0
	v_add3_u32 v34, v35, v34, s14
	v_and_or_b32 v34, v34, s15, v0
	v_bfe_u32 v0, v36, 16, 1
	v_add3_u32 v0, v36, v0, s14
	v_bfe_u32 v35, v37, 16, 1
	v_pk_mul_f32 v[30:31], v[30:31], v[176:177] op_sel_hi:[1,0]
	v_lshrrev_b32_e32 v0, 16, v0
	v_add3_u32 v35, v37, v35, s14
	v_pk_fma_f32 v[30:31], v[160:161], v[30:31], v[82:83]
	v_and_or_b32 v35, v35, s15, v0
	v_bfe_u32 v0, v30, 16, 1
	v_pk_mul_f32 v[32:33], v[32:33], v[176:177] op_sel_hi:[1,0]
	v_add3_u32 v0, v30, v0, s14
	v_bfe_u32 v30, v31, 16, 1
	v_pk_fma_f32 v[32:33], v[144:145], v[32:33], v[84:85]
	v_lshrrev_b32_e32 v0, 16, v0
	v_add3_u32 v30, v31, v30, s14
	v_and_or_b32 v30, v30, s15, v0
	v_bfe_u32 v0, v32, 16, 1
	v_pk_mul_f32 v[26:27], v[26:27], v[174:175] op_sel_hi:[1,0]
	v_add3_u32 v0, v32, v0, s14
	v_bfe_u32 v31, v33, 16, 1
	v_pk_fma_f32 v[26:27], v[160:161], v[26:27], v[82:83]
	v_lshrrev_b32_e32 v0, 16, v0
	v_add3_u32 v31, v33, v31, s14
	v_and_or_b32 v31, v31, s15, v0
	v_bfe_u32 v0, v26, 16, 1
	v_pk_mul_f32 v[28:29], v[28:29], v[174:175] op_sel_hi:[1,0]
	v_add3_u32 v0, v26, v0, s14
	v_bfe_u32 v26, v27, 16, 1
	v_pk_fma_f32 v[28:29], v[144:145], v[28:29], v[84:85]
	v_lshrrev_b32_e32 v0, 16, v0
	v_add3_u32 v26, v27, v26, s14
	v_and_or_b32 v26, v26, s15, v0
	v_bfe_u32 v0, v28, 16, 1
	v_add3_u32 v0, v28, v0, s14
	v_bfe_u32 v27, v29, 16, 1
	v_pk_mul_f32 v[22:23], v[22:23], v[176:177] op_sel_hi:[1,0]
	v_lshrrev_b32_e32 v0, 16, v0
	v_add3_u32 v27, v29, v27, s14
	v_pk_fma_f32 v[22:23], v[164:165], v[22:23], v[86:87]
	v_and_or_b32 v27, v27, s15, v0
	v_bfe_u32 v0, v22, 16, 1
	v_pk_mul_f32 v[24:25], v[24:25], v[176:177] op_sel_hi:[1,0]
	v_add3_u32 v0, v22, v0, s14
	v_bfe_u32 v22, v23, 16, 1
	v_pk_fma_f32 v[24:25], v[162:163], v[24:25], v[88:89]
	v_lshrrev_b32_e32 v0, 16, v0
	v_add3_u32 v22, v23, v22, s14
	v_and_or_b32 v22, v22, s15, v0
	v_bfe_u32 v0, v24, 16, 1
	v_pk_mul_f32 v[18:19], v[18:19], v[174:175] op_sel_hi:[1,0]
	v_add3_u32 v0, v24, v0, s14
	v_bfe_u32 v23, v25, 16, 1
	v_pk_fma_f32 v[18:19], v[164:165], v[18:19], v[86:87]
	v_lshrrev_b32_e32 v0, 16, v0
	v_add3_u32 v23, v25, v23, s14
	v_and_or_b32 v23, v23, s15, v0
	v_bfe_u32 v0, v18, 16, 1
	v_pk_mul_f32 v[20:21], v[20:21], v[174:175] op_sel_hi:[1,0]
	v_add3_u32 v0, v18, v0, s14
	v_bfe_u32 v18, v19, 16, 1
	v_pk_fma_f32 v[20:21], v[162:163], v[20:21], v[88:89]
	v_lshrrev_b32_e32 v0, 16, v0
	v_add3_u32 v18, v19, v18, s14
	v_and_or_b32 v18, v18, s15, v0
	v_bfe_u32 v0, v20, 16, 1
	v_add3_u32 v0, v20, v0, s14
	v_bfe_u32 v19, v21, 16, 1
	v_pk_mul_f32 v[14:15], v[14:15], v[176:177] op_sel_hi:[1,0]
	v_lshrrev_b32_e32 v0, 16, v0
	v_add3_u32 v19, v21, v19, s14
	v_pk_fma_f32 v[14:15], v[168:169], v[14:15], v[90:91]
	v_and_or_b32 v19, v19, s15, v0
	v_bfe_u32 v0, v14, 16, 1
	v_pk_mul_f32 v[16:17], v[16:17], v[176:177] op_sel_hi:[1,0]
	v_add3_u32 v0, v14, v0, s14
	v_bfe_u32 v14, v15, 16, 1
	v_pk_fma_f32 v[16:17], v[166:167], v[16:17], v[92:93]
	v_lshrrev_b32_e32 v0, 16, v0
	v_add3_u32 v14, v15, v14, s14
	v_and_or_b32 v14, v14, s15, v0
	v_bfe_u32 v0, v16, 16, 1
	v_pk_mul_f32 v[10:11], v[10:11], v[174:175] op_sel_hi:[1,0]
	v_add3_u32 v0, v16, v0, s14
	v_bfe_u32 v15, v17, 16, 1
	v_pk_fma_f32 v[10:11], v[168:169], v[10:11], v[90:91]
	v_lshrrev_b32_e32 v0, 16, v0
	v_add3_u32 v15, v17, v15, s14
	v_and_or_b32 v15, v15, s15, v0
	v_bfe_u32 v0, v10, 16, 1
	v_pk_mul_f32 v[12:13], v[12:13], v[174:175] op_sel_hi:[1,0]
	v_add3_u32 v0, v10, v0, s14
	v_bfe_u32 v10, v11, 16, 1
	v_pk_fma_f32 v[12:13], v[166:167], v[12:13], v[92:93]
	v_lshrrev_b32_e32 v0, 16, v0
	v_add3_u32 v10, v11, v10, s14
	v_and_or_b32 v10, v10, s15, v0
	v_bfe_u32 v0, v12, 16, 1
	v_add3_u32 v0, v12, v0, s14
	v_bfe_u32 v11, v13, 16, 1
	v_pk_mul_f32 v[6:7], v[6:7], v[176:177] op_sel_hi:[1,0]
	v_lshrrev_b32_e32 v0, 16, v0
	v_add3_u32 v11, v13, v11, s14
	s_waitcnt vmcnt(0)
	v_pk_fma_f32 v[6:7], v[172:173], v[6:7], v[94:95]
	v_and_or_b32 v11, v11, s15, v0
	v_bfe_u32 v0, v6, 16, 1
	v_pk_mul_f32 v[8:9], v[8:9], v[176:177] op_sel_hi:[1,0]
	v_add3_u32 v0, v6, v0, s14
	v_bfe_u32 v6, v7, 16, 1
	v_pk_fma_f32 v[8:9], v[170:171], v[8:9], v[96:97]
	v_lshrrev_b32_e32 v0, 16, v0
	v_add3_u32 v6, v7, v6, s14
	v_and_or_b32 v6, v6, s15, v0
	v_bfe_u32 v0, v8, 16, 1
	v_pk_mul_f32 v[2:3], v[2:3], v[174:175] op_sel_hi:[1,0]
	v_add3_u32 v0, v8, v0, s14
	v_bfe_u32 v7, v9, 16, 1
	v_pk_fma_f32 v[2:3], v[172:173], v[2:3], v[94:95]
	v_lshrrev_b32_e32 v0, 16, v0
	v_add3_u32 v7, v9, v7, s14
	v_and_or_b32 v7, v7, s15, v0
	v_bfe_u32 v0, v2, 16, 1
	v_pk_mul_f32 v[4:5], v[4:5], v[174:175] op_sel_hi:[1,0]
	v_add3_u32 v0, v2, v0, s14
	v_bfe_u32 v2, v3, 16, 1
	v_pk_fma_f32 v[4:5], v[170:171], v[4:5], v[96:97]
	v_lshrrev_b32_e32 v0, 16, v0
	v_add3_u32 v2, v3, v2, s14
	v_and_or_b32 v2, v2, s15, v0
	v_bfe_u32 v0, v4, 16, 1
	v_add3_u32 v0, v4, v0, s14
	v_bfe_u32 v3, v5, 16, 1
	v_lshrrev_b32_e32 v0, 16, v0
	v_add3_u32 v3, v5, v3, s14
	v_and_or_b32 v3, v3, s15, v0
	v_subrev_u32_e32 v0, s10, v197
	v_add_u32_e32 v197, 0x800, v0
	v_cmp_lt_u32_e32 vcc, s9, v197
	s_or_b64 s[46:47], vcc, s[46:47]
	global_store_dwordx2 v[64:65], v[62:63], off
	global_store_dwordx2 v[60:61], v[58:59], off
	global_store_dwordx2 v[64:65], v[54:55], off offset:512
	global_store_dwordx2 v[60:61], v[50:51], off offset:512
	global_store_dwordx2 v[64:65], v[46:47], off offset:1024
	global_store_dwordx2 v[60:61], v[42:43], off offset:1024
	global_store_dwordx2 v[64:65], v[38:39], off offset:1536
	global_store_dwordx2 v[60:61], v[34:35], off offset:1536
	global_store_dwordx2 v[64:65], v[30:31], off offset:2048
	global_store_dwordx2 v[60:61], v[26:27], off offset:2048
	global_store_dwordx2 v[64:65], v[22:23], off offset:2560
	global_store_dwordx2 v[60:61], v[18:19], off offset:2560
	global_store_dwordx2 v[64:65], v[14:15], off offset:3072
	global_store_dwordx2 v[60:61], v[10:11], off offset:3072
	global_store_dwordx2 v[64:65], v[6:7], off offset:3584
	global_store_dwordx2 v[60:61], v[2:3], off offset:3584
	s_andn2_b64 exec, exec, s[46:47]
	s_cbranch_execnz .LBB0_204
